# previous + KV-copy burst/pool stores and sample-attention row-copy stores as sc0 sc1 nt (write-through streaming)
# baseline (speedup 1.0000x reference)
.LBB0_167:
	v_lshl_add_u64 v[78:79], v[74:75], 0, s[6:7]
	s_mov_b64 s[2:3], 0xc000
	v_lshl_add_u64 v[82:83], v[78:79], 0, s[2:3]
	s_mov_b64 s[2:3], 0xe000
	global_load_dwordx4 v[34:37], v[82:83], off sc0 sc1 nt
	v_lshl_add_u64 v[84:85], v[78:79], 0, s[2:3]
	s_mov_b64 s[2:3], 0x10000
	global_load_dwordx4 v[30:33], v[84:85], off sc0 sc1 nt
	v_lshl_add_u64 v[86:87], v[78:79], 0, s[2:3]
	s_mov_b64 s[2:3], 0x12000
	global_load_dwordx4 v[26:29], v[86:87], off sc0 sc1 nt
	v_lshl_add_u64 v[88:89], v[78:79], 0, s[2:3]
	s_mov_b64 s[2:3], 0x14000
	global_load_dwordx4 v[22:25], v[88:89], off sc0 sc1 nt
	v_lshl_add_u64 v[90:91], v[78:79], 0, s[2:3]
	s_mov_b64 s[2:3], 0x16000
	global_load_dwordx4 v[18:21], v[90:91], off sc0 sc1 nt
	v_lshl_add_u64 v[92:93], v[78:79], 0, s[2:3]
	s_mov_b64 s[2:3], 0x18000
	global_load_dwordx4 v[14:17], v[92:93], off sc0 sc1 nt
	v_lshl_add_u64 v[94:95], v[78:79], 0, s[2:3]
	global_load_dwordx4 v[10:13], v[94:95], off sc0 sc1 nt
	v_lshl_add_u64 v[96:97], v[78:79], 0, s[12:13]
	global_load_dwordx4 v[6:9], v[96:97], off sc0 sc1 nt
	v_lshl_add_u64 v[98:99], v[78:79], 0, s[14:15]
	global_load_dwordx4 v[2:5], v[98:99], off sc0 sc1 nt
	v_lshl_add_u64 v[100:101], v[78:79], 0, s[24:25]
	global_load_dwordx4 v[70:73], v[100:101], off sc0 sc1 nt
	v_lshl_add_u64 v[102:103], v[78:79], 0, s[26:27]
	global_load_dwordx4 v[66:69], v[102:103], off sc0 sc1 nt
	v_lshl_add_u64 v[104:105], v[78:79], 0, s[28:29]
	global_load_dwordx4 v[62:65], v[104:105], off sc0 sc1 nt
	v_lshl_add_u64 v[106:107], v[78:79], 0, s[34:35]
	global_load_dwordx4 v[58:61], v[106:107], off sc0 sc1 nt
	v_lshl_add_u64 v[108:109], v[78:79], 0, s[42:43]
	global_load_dwordx4 v[54:57], v[108:109], off sc0 sc1 nt
	v_lshl_add_u64 v[110:111], v[78:79], 0, s[46:47]
	global_load_dwordx4 v[50:53], v[110:111], off sc0 sc1 nt
	v_lshl_add_u64 v[112:113], v[78:79], 0, s[56:57]
	global_load_dwordx4 v[46:49], v[112:113], off sc0 sc1 nt
	v_lshl_add_u64 v[114:115], v[78:79], 0, s[58:59]
	global_load_dwordx4 v[42:45], v[114:115], off sc0 sc1 nt
	v_lshl_add_u64 v[78:79], v[78:79], 0, s[60:61]
	global_load_dwordx4 v[38:41], v[78:79], off sc0 sc1 nt
	v_lshl_add_u64 v[80:81], v[76:77], 0, s[6:7]
	s_waitcnt vmcnt(9)
	v_lshl_add_u64 v[116:117], v[80:81], 0, s[64:65]
	global_store_dwordx4 v[116:117], v[34:37], off sc0 sc1 nt
	s_nop 1
	v_lshl_add_u64 v[118:119], v[80:81], 0, s[66:67]
	global_store_dwordx4 v[118:119], v[30:33], off sc0 sc1 nt
	s_nop 1
	v_lshl_add_u64 v[120:121], v[80:81], 0, s[68:69]
	global_store_dwordx4 v[120:121], v[26:29], off sc0 sc1 nt
	s_nop 1
	v_lshl_add_u64 v[122:123], v[80:81], 0, s[0:1]
	global_store_dwordx4 v[122:123], v[22:25], off sc0 sc1 nt
	s_nop 1
	v_lshl_add_u64 v[124:125], v[80:81], 0, s[70:71]
	global_store_dwordx4 v[124:125], v[18:21], off sc0 sc1 nt
	s_nop 1
	v_lshl_add_u64 v[126:127], v[80:81], 0, s[72:73]
	global_store_dwordx4 v[126:127], v[14:17], off sc0 sc1 nt
	s_nop 1
	v_lshl_add_u64 v[128:129], v[80:81], 0, s[74:75]
	global_store_dwordx4 v[128:129], v[10:13], off sc0 sc1 nt
	s_nop 1
	v_lshl_add_u64 v[130:131], v[80:81], 0, s[76:77]
	global_store_dwordx4 v[130:131], v[6:9], off sc0 sc1 nt
	s_nop 1
	v_lshl_add_u64 v[132:133], v[80:81], 0, s[78:79]
	global_store_dwordx4 v[132:133], v[2:5], off sc0 sc1 nt
	s_nop 1
	s_waitcnt vmcnt(0)
	v_lshl_add_u64 v[134:135], v[80:81], 0, s[80:81]
	global_store_dwordx4 v[134:135], v[70:73], off sc0 sc1 nt
	s_nop 1
	v_lshl_add_u64 v[136:137], v[80:81], 0, s[82:83]
	global_store_dwordx4 v[136:137], v[66:69], off sc0 sc1 nt
	s_nop 1
	v_lshl_add_u64 v[138:139], v[80:81], 0, s[84:85]
	global_store_dwordx4 v[138:139], v[62:65], off sc0 sc1 nt
	s_nop 1
	v_lshl_add_u64 v[140:141], v[80:81], 0, s[86:87]
	global_store_dwordx4 v[140:141], v[58:61], off sc0 sc1 nt
	s_nop 1
	v_lshl_add_u64 v[142:143], v[80:81], 0, s[88:89]
	global_store_dwordx4 v[142:143], v[54:57], off sc0 sc1 nt
	s_nop 1
	v_lshl_add_u64 v[144:145], v[80:81], 0, s[90:91]
	global_store_dwordx4 v[144:145], v[50:53], off sc0 sc1 nt
	s_nop 1
	v_lshl_add_u64 v[146:147], v[80:81], 0, s[92:93]
	global_store_dwordx4 v[146:147], v[46:49], off sc0 sc1 nt
	s_nop 1
	v_lshl_add_u64 v[148:149], v[80:81], 0, s[94:95]
	global_store_dwordx4 v[148:149], v[42:45], off sc0 sc1 nt
	s_nop 1
	s_add_u32 s6, s6, 0x30000
	v_lshl_add_u64 v[80:81], v[80:81], 0, s[96:97]
	global_store_dwordx4 v[80:81], v[38:41], off sc0 sc1 nt
	s_nop 1
	s_addc_u32 s7, s7, 0
	s_cmp_lg_u32 s6, 0x120000
	s_cbranch_scc1 .LBB0_167
	s_waitcnt vmcnt(0)
	v_readlane_b32 s50, v248, 42
	v_readlane_b32 s51, v248, 43

.LBB0_339:
	v_lshl_add_u64 v[74:75], v[166:167], 0, s[8:9]
	s_mov_b64 s[0:1], 0xc000
	v_lshl_add_u64 v[76:77], v[74:75], 0, s[0:1]
	global_load_dwordx4 v[34:37], v[76:77], off sc0 sc1 nt
	s_mov_b64 s[0:1], 0xe000
	v_lshl_add_u64 v[76:77], v[74:75], 0, s[0:1]
	global_load_dwordx4 v[30:33], v[76:77], off sc0 sc1 nt
	s_mov_b64 s[0:1], 0x10000
	v_lshl_add_u64 v[76:77], v[74:75], 0, s[0:1]
	global_load_dwordx4 v[26:29], v[76:77], off sc0 sc1 nt
	s_mov_b64 s[0:1], 0x12000
	v_lshl_add_u64 v[76:77], v[74:75], 0, s[0:1]
	global_load_dwordx4 v[22:25], v[76:77], off sc0 sc1 nt
	s_mov_b64 s[0:1], 0x14000
	v_lshl_add_u64 v[76:77], v[74:75], 0, s[0:1]
	global_load_dwordx4 v[18:21], v[76:77], off sc0 sc1 nt
	s_mov_b64 s[0:1], 0x16000
	v_lshl_add_u64 v[76:77], v[74:75], 0, s[0:1]
	global_load_dwordx4 v[14:17], v[76:77], off sc0 sc1 nt
	s_mov_b64 s[0:1], 0x18000
	v_lshl_add_u64 v[76:77], v[74:75], 0, s[0:1]
	global_load_dwordx4 v[10:13], v[76:77], off sc0 sc1 nt
	s_mov_b64 s[0:1], 0x1a000
	v_lshl_add_u64 v[76:77], v[74:75], 0, s[0:1]
	global_load_dwordx4 v[6:9], v[76:77], off sc0 sc1 nt
	s_mov_b64 s[0:1], 0x1c000
	v_lshl_add_u64 v[76:77], v[74:75], 0, s[0:1]
	global_load_dwordx4 v[2:5], v[76:77], off sc0 sc1 nt
	s_mov_b64 s[0:1], 0x1e000
	v_lshl_add_u64 v[76:77], v[74:75], 0, s[0:1]
	global_load_dwordx4 v[70:73], v[76:77], off sc0 sc1 nt
	v_lshl_add_u64 v[76:77], v[74:75], 0, s[96:97]
	global_load_dwordx4 v[66:69], v[76:77], off sc0 sc1 nt
	s_mov_b64 s[0:1], 0x22000
	v_lshl_add_u64 v[76:77], v[74:75], 0, s[0:1]
	global_load_dwordx4 v[62:65], v[76:77], off sc0 sc1 nt
	v_lshl_add_u64 v[76:77], v[74:75], 0, s[98:99]
	global_load_dwordx4 v[58:61], v[76:77], off sc0 sc1 nt
	s_mov_b64 s[0:1], 0x26000
	v_lshl_add_u64 v[76:77], v[74:75], 0, s[0:1]
	global_load_dwordx4 v[54:57], v[76:77], off sc0 sc1 nt
	v_lshl_add_u64 v[76:77], v[74:75], 0, s[90:91]
	global_load_dwordx4 v[50:53], v[76:77], off sc0 sc1 nt
	s_mov_b64 s[0:1], 0x2a000
	v_lshl_add_u64 v[76:77], v[74:75], 0, s[0:1]
	global_load_dwordx4 v[46:49], v[76:77], off sc0 sc1 nt
	v_lshl_add_u64 v[76:77], v[74:75], 0, s[88:89]
	global_load_dwordx4 v[42:45], v[76:77], off sc0 sc1 nt
	s_mov_b64 s[0:1], 0x2e000
	v_lshl_add_u64 v[74:75], v[74:75], 0, s[0:1]
	global_load_dwordx4 v[38:41], v[74:75], off sc0 sc1 nt
	s_waitcnt vmcnt(9)
	v_lshl_add_u64 v[74:75], v[168:169], 0, s[8:9]
	s_mov_b64 s[0:1], 0xa31c000
	v_lshl_add_u64 v[76:77], v[74:75], 0, s[0:1]
	global_store_dwordx4 v[76:77], v[34:37], off sc0 sc1 nt
	s_nop 1
	s_mov_b64 s[0:1], 0xa31e000
	v_lshl_add_u64 v[76:77], v[74:75], 0, s[0:1]
	global_store_dwordx4 v[76:77], v[30:33], off sc0 sc1 nt
	s_nop 1
	s_mov_b64 s[0:1], 0xa320000
	v_lshl_add_u64 v[76:77], v[74:75], 0, s[0:1]
	global_store_dwordx4 v[76:77], v[26:29], off sc0 sc1 nt
	s_nop 1
	s_mov_b64 s[0:1], 0xa322000
	v_lshl_add_u64 v[76:77], v[74:75], 0, s[0:1]
	global_store_dwordx4 v[76:77], v[22:25], off sc0 sc1 nt
	s_nop 1
	s_mov_b64 s[0:1], 0xa324000
	v_lshl_add_u64 v[76:77], v[74:75], 0, s[0:1]
	global_store_dwordx4 v[76:77], v[18:21], off sc0 sc1 nt
	s_nop 1
	s_mov_b64 s[0:1], 0xa326000
	v_lshl_add_u64 v[76:77], v[74:75], 0, s[0:1]
	global_store_dwordx4 v[76:77], v[14:17], off sc0 sc1 nt
	s_nop 1
	s_mov_b64 s[0:1], 0xa328000
	v_lshl_add_u64 v[76:77], v[74:75], 0, s[0:1]
	global_store_dwordx4 v[76:77], v[10:13], off sc0 sc1 nt
	s_nop 1
	s_mov_b64 s[0:1], 0xa32a000
	v_lshl_add_u64 v[76:77], v[74:75], 0, s[0:1]
	global_store_dwordx4 v[76:77], v[6:9], off sc0 sc1 nt
	s_nop 1
	s_mov_b64 s[0:1], 0xa32c000
	v_lshl_add_u64 v[76:77], v[74:75], 0, s[0:1]
	global_store_dwordx4 v[76:77], v[2:5], off sc0 sc1 nt
	s_nop 1
	s_waitcnt vmcnt(0)
	s_mov_b64 s[0:1], 0xa32e000
	v_lshl_add_u64 v[76:77], v[74:75], 0, s[0:1]
	global_store_dwordx4 v[76:77], v[70:73], off sc0 sc1 nt
	s_nop 1
	s_mov_b64 s[0:1], 0xa330000
	v_lshl_add_u64 v[76:77], v[74:75], 0, s[0:1]
	global_store_dwordx4 v[76:77], v[66:69], off sc0 sc1 nt
	s_nop 1
	s_mov_b64 s[0:1], 0xa332000
	v_lshl_add_u64 v[76:77], v[74:75], 0, s[0:1]
	global_store_dwordx4 v[76:77], v[62:65], off sc0 sc1 nt
	s_nop 1
	s_mov_b64 s[0:1], 0xa334000
	v_lshl_add_u64 v[76:77], v[74:75], 0, s[0:1]
	global_store_dwordx4 v[76:77], v[58:61], off sc0 sc1 nt
	s_nop 1
	s_mov_b64 s[0:1], 0xa336000
	v_lshl_add_u64 v[76:77], v[74:75], 0, s[0:1]
	global_store_dwordx4 v[76:77], v[54:57], off sc0 sc1 nt
	s_nop 1
	s_mov_b64 s[0:1], 0xa338000
	v_lshl_add_u64 v[76:77], v[74:75], 0, s[0:1]
	global_store_dwordx4 v[76:77], v[50:53], off sc0 sc1 nt
	s_nop 1
	s_mov_b64 s[0:1], 0xa33a000
	v_lshl_add_u64 v[76:77], v[74:75], 0, s[0:1]
	global_store_dwordx4 v[76:77], v[46:49], off sc0 sc1 nt
	s_nop 1
	s_mov_b64 s[0:1], 0xa33c000
	v_lshl_add_u64 v[76:77], v[74:75], 0, s[0:1]
	global_store_dwordx4 v[76:77], v[42:45], off sc0 sc1 nt
	s_nop 1
	s_mov_b64 s[0:1], 0xa33e000
	v_lshl_add_u64 v[74:75], v[74:75], 0, s[0:1]
	global_store_dwordx4 v[74:75], v[38:41], off sc0 sc1 nt
	s_nop 1
	s_add_u32 s8, s8, 0x30000
	s_addc_u32 s9, s9, 0
	s_cmp_lg_u32 s8, 0x120000
	s_cbranch_scc1 .LBB0_339
	s_waitcnt vmcnt(0)
	s_mov_b64 s[20:21], -1
	s_branch .LBB0_172

.LBB0_366:
	v_lshl_add_u64 v[78:79], v[74:75], 0, s[6:7]
	s_mov_b64 s[0:1], 0xc000
	v_lshl_add_u64 v[80:81], v[78:79], 0, s[0:1]
	global_load_dwordx4 v[34:37], v[80:81], off sc0 sc1 nt
	s_mov_b64 s[0:1], 0xe000
	v_lshl_add_u64 v[80:81], v[78:79], 0, s[0:1]
	global_load_dwordx4 v[30:33], v[80:81], off sc0 sc1 nt
	s_mov_b64 s[0:1], 0x10000
	v_lshl_add_u64 v[80:81], v[78:79], 0, s[0:1]
	global_load_dwordx4 v[26:29], v[80:81], off sc0 sc1 nt
	v_lshl_add_u64 v[80:81], v[78:79], 0, s[8:9]
	global_load_dwordx4 v[22:25], v[80:81], off sc0 sc1 nt
	v_lshl_add_u64 v[80:81], v[78:79], 0, s[10:11]
	global_load_dwordx4 v[18:21], v[80:81], off sc0 sc1 nt
	v_lshl_add_u64 v[80:81], v[78:79], 0, s[12:13]
	global_load_dwordx4 v[14:17], v[80:81], off sc0 sc1 nt
	v_lshl_add_u64 v[80:81], v[78:79], 0, s[24:25]
	global_load_dwordx4 v[10:13], v[80:81], off sc0 sc1 nt
	v_lshl_add_u64 v[80:81], v[78:79], 0, s[26:27]
	global_load_dwordx4 v[6:9], v[80:81], off sc0 sc1 nt
	v_lshl_add_u64 v[80:81], v[78:79], 0, s[28:29]
	global_load_dwordx4 v[2:5], v[80:81], off sc0 sc1 nt
	v_lshl_add_u64 v[80:81], v[78:79], 0, s[34:35]
	global_load_dwordx4 v[70:73], v[80:81], off sc0 sc1 nt
	v_lshl_add_u64 v[80:81], v[78:79], 0, s[42:43]
	global_load_dwordx4 v[66:69], v[80:81], off sc0 sc1 nt
	v_lshl_add_u64 v[80:81], v[78:79], 0, s[46:47]
	global_load_dwordx4 v[62:65], v[80:81], off sc0 sc1 nt
	v_lshl_add_u64 v[80:81], v[78:79], 0, s[56:57]
	global_load_dwordx4 v[58:61], v[80:81], off sc0 sc1 nt
	v_lshl_add_u64 v[80:81], v[78:79], 0, s[58:59]
	global_load_dwordx4 v[54:57], v[80:81], off sc0 sc1 nt
	v_lshl_add_u64 v[80:81], v[78:79], 0, s[60:61]
	global_load_dwordx4 v[50:53], v[80:81], off sc0 sc1 nt
	v_lshl_add_u64 v[80:81], v[78:79], 0, s[62:63]
	global_load_dwordx4 v[46:49], v[80:81], off sc0 sc1 nt
	v_lshl_add_u64 v[80:81], v[78:79], 0, s[64:65]
	global_load_dwordx4 v[42:45], v[80:81], off sc0 sc1 nt
	v_lshl_add_u64 v[78:79], v[78:79], 0, s[66:67]
	global_load_dwordx4 v[38:41], v[78:79], off sc0 sc1 nt
	s_waitcnt vmcnt(9)
	v_lshl_add_u64 v[78:79], v[76:77], 0, s[6:7]
	v_lshl_add_u64 v[80:81], v[78:79], 0, s[68:69]
	global_store_dwordx4 v[80:81], v[34:37], off sc0 sc1 nt
	s_nop 1
	v_lshl_add_u64 v[80:81], v[78:79], 0, s[70:71]
	global_store_dwordx4 v[80:81], v[30:33], off sc0 sc1 nt
	s_nop 1
	v_lshl_add_u64 v[80:81], v[78:79], 0, s[72:73]
	global_store_dwordx4 v[80:81], v[26:29], off sc0 sc1 nt
	s_nop 1
	v_lshl_add_u64 v[80:81], v[78:79], 0, s[74:75]
	global_store_dwordx4 v[80:81], v[22:25], off sc0 sc1 nt
	s_nop 1
	v_lshl_add_u64 v[80:81], v[78:79], 0, s[76:77]
	global_store_dwordx4 v[80:81], v[18:21], off sc0 sc1 nt
	s_nop 1
	v_lshl_add_u64 v[80:81], v[78:79], 0, s[78:79]
	global_store_dwordx4 v[80:81], v[14:17], off sc0 sc1 nt
	s_nop 1
	v_lshl_add_u64 v[80:81], v[78:79], 0, s[80:81]
	global_store_dwordx4 v[80:81], v[10:13], off sc0 sc1 nt
	s_nop 1
	v_lshl_add_u64 v[80:81], v[78:79], 0, s[82:83]
	global_store_dwordx4 v[80:81], v[6:9], off sc0 sc1 nt
	s_nop 1
	v_lshl_add_u64 v[80:81], v[78:79], 0, s[84:85]
	global_store_dwordx4 v[80:81], v[2:5], off sc0 sc1 nt
	s_nop 1
	s_waitcnt vmcnt(0)
	v_lshl_add_u64 v[80:81], v[78:79], 0, s[86:87]
	global_store_dwordx4 v[80:81], v[70:73], off sc0 sc1 nt
	s_nop 1
	v_lshl_add_u64 v[80:81], v[78:79], 0, s[88:89]
	global_store_dwordx4 v[80:81], v[66:69], off sc0 sc1 nt
	s_nop 1
	v_lshl_add_u64 v[80:81], v[78:79], 0, s[90:91]
	global_store_dwordx4 v[80:81], v[62:65], off sc0 sc1 nt
	s_nop 1
	v_lshl_add_u64 v[80:81], v[78:79], 0, s[92:93]
	global_store_dwordx4 v[80:81], v[58:61], off sc0 sc1 nt
	s_nop 1
	v_lshl_add_u64 v[80:81], v[78:79], 0, s[94:95]
	global_store_dwordx4 v[80:81], v[54:57], off sc0 sc1 nt
	s_nop 1
	v_lshl_add_u64 v[80:81], v[78:79], 0, s[96:97]
	global_store_dwordx4 v[80:81], v[50:53], off sc0 sc1 nt
	s_nop 1
	v_lshl_add_u64 v[80:81], v[78:79], 0, s[98:99]
	global_store_dwordx4 v[80:81], v[46:49], off sc0 sc1 nt
	s_nop 1
	v_lshl_add_u64 v[80:81], v[78:79], 0, vcc
	global_store_dwordx4 v[80:81], v[42:45], off sc0 sc1 nt
	s_nop 1
	v_lshl_add_u64 v[78:79], v[78:79], 0, s[14:15]
	global_store_dwordx4 v[78:79], v[38:41], off sc0 sc1 nt
	s_nop 1
	s_add_u32 s6, s6, 0x30000
	s_addc_u32 s7, s7, 0
	s_cmp_lg_u32 s6, 0x120000
	s_cbranch_scc1 .LBB0_366
	s_waitcnt vmcnt(0)

.LBB0_380:
	s_or_b64 exec, exec, s[10:11]
	s_waitcnt lgkmcnt(0)
	s_barrier
	ds_read_b32 v8, v6
	s_mov_b64 s[34:35], -1
	s_mov_b64 s[10:11], -1
	s_waitcnt lgkmcnt(0)
	v_readfirstlane_b32 s9, v8
	s_cmpk_gt_i32 s9, 0x5ff
	s_cbranch_scc1 .LBB0_369
	s_mul_hi_i32 s10, s9, 0x2aaaaaab
	s_lshr_b32 s11, s10, 31
	s_add_i32 s16, s10, s11
	s_mul_i32 s10, s16, 6
	s_sub_i32 s9, s9, s10
	s_ashr_i32 s17, s16, 3
	s_add_i32 s9, s9, 6
	v_mad_i64_i32 v[8:9], s[10:11], s17, v7, v[2:3]
	s_and_b32 s16, s16, 7
	v_mad_i64_i32 v[80:81], s[10:11], s17, v7, v[4:5]
	s_mul_i32 s16, s16, 0x24000
	s_mul_hi_u32 s11, s9, 0x3000
	s_mulk_i32 s9, 0x3000
	s_add_u32 s10, s9, s16
	s_addc_u32 s11, s11, 0
	s_lshl_b64 s[16:17], s[10:11], 4
	s_mov_b32 s10, s8
	s_mov_b32 s11, s8
	v_lshl_add_u64 v[48:49], v[8:9], 0, s[0:1]
	s_mov_b32 s9, s8
	v_mov_b64_e32 v[14:15], s[10:11]
	s_waitcnt vmcnt(0)
	v_lshl_add_u64 v[44:45], v[48:49], 0, s[16:17]
	v_mov_b64_e32 v[12:13], s[8:9]
	v_mov_b64_e32 v[18:19], s[10:11]
	global_load_dwordx4 v[12:15], v[44:45], off sc0 sc1 nt
	v_lshl_add_u64 v[20:21], v[44:45], 0, s[2:3]
	v_mov_b64_e32 v[16:17], s[8:9]
	global_load_dwordx4 v[16:19], v[20:21], off sc0 sc1 nt
	v_mov_b64_e32 v[22:23], s[10:11]
	v_lshl_add_u64 v[24:25], v[44:45], 0, s[6:7]
	v_mov_b64_e32 v[20:21], s[8:9]
	global_load_dwordx4 v[20:23], v[24:25], off sc0 sc1 nt
	v_mov_b64_e32 v[26:27], s[10:11]
	v_lshl_add_u64 v[28:29], v[44:45], 0, s[12:13]
	v_mov_b64_e32 v[24:25], s[8:9]
	global_load_dwordx4 v[24:27], v[28:29], off sc0 sc1 nt
	v_mov_b64_e32 v[30:31], s[10:11]
	v_lshl_add_u64 v[32:33], v[44:45], 0, s[14:15]
	v_mov_b64_e32 v[28:29], s[8:9]
	global_load_dwordx4 v[28:31], v[32:33], off sc0 sc1 nt
	v_mov_b64_e32 v[34:35], s[10:11]
	v_lshl_add_u64 v[36:37], v[44:45], 0, s[24:25]
	v_mov_b64_e32 v[32:33], s[8:9]
	global_load_dwordx4 v[32:35], v[36:37], off sc0 sc1 nt
	v_mov_b64_e32 v[38:39], s[10:11]
	v_lshl_add_u64 v[40:41], v[44:45], 0, s[0:1]
	v_mov_b64_e32 v[36:37], s[8:9]
	global_load_dwordx4 v[36:39], v[40:41], off sc0 sc1 nt
	v_mov_b64_e32 v[42:43], s[10:11]
	v_lshl_add_u64 v[46:47], v[44:45], 0, s[26:27]
	v_mov_b64_e32 v[40:41], s[8:9]
	v_mov_b64_e32 v[8:9], s[8:9]
	global_load_dwordx4 v[40:43], v[46:47], off sc0 sc1 nt
	v_lshl_add_u64 v[50:51], v[44:45], 0, s[28:29]
	v_mov_b64_e32 v[46:47], s[10:11]
	v_mov_b64_e32 v[10:11], s[10:11]
	v_mov_b64_e32 v[44:45], s[8:9]
	s_add_u32 s10, s16, 0x12000
	s_addc_u32 s11, s17, 0
	global_load_dwordx4 v[44:47], v[50:51], off sc0 sc1 nt
	v_lshl_add_u64 v[82:83], v[48:49], 0, s[10:11]
	v_mov_b64_e32 v[50:51], v[10:11]
	v_mov_b64_e32 v[48:49], v[8:9]
	v_mov_b64_e32 v[54:55], v[10:11]
	global_load_dwordx4 v[48:51], v[82:83], off sc0 sc1 nt
	v_lshl_add_u64 v[56:57], v[82:83], 0, s[2:3]
	v_mov_b64_e32 v[52:53], v[8:9]
	global_load_dwordx4 v[52:55], v[56:57], off sc0 sc1 nt
	v_mov_b64_e32 v[58:59], v[10:11]
	v_lshl_add_u64 v[60:61], v[82:83], 0, s[6:7]
	v_mov_b64_e32 v[56:57], v[8:9]
	global_load_dwordx4 v[56:59], v[60:61], off sc0 sc1 nt
	v_mov_b64_e32 v[62:63], v[10:11]
	v_lshl_add_u64 v[64:65], v[82:83], 0, s[12:13]
	v_mov_b64_e32 v[60:61], v[8:9]
	global_load_dwordx4 v[60:63], v[64:65], off sc0 sc1 nt
	v_mov_b64_e32 v[66:67], v[10:11]
	v_lshl_add_u64 v[68:69], v[82:83], 0, s[14:15]
	v_mov_b64_e32 v[64:65], v[8:9]
	global_load_dwordx4 v[64:67], v[68:69], off sc0 sc1 nt
	v_mov_b64_e32 v[70:71], v[10:11]
	v_lshl_add_u64 v[72:73], v[82:83], 0, s[24:25]
	v_mov_b64_e32 v[68:69], v[8:9]
	global_load_dwordx4 v[68:71], v[72:73], off sc0 sc1 nt
	v_mov_b64_e32 v[74:75], v[10:11]
	v_lshl_add_u64 v[76:77], v[82:83], 0, s[0:1]
	v_mov_b64_e32 v[72:73], v[8:9]
	global_load_dwordx4 v[72:75], v[76:77], off sc0 sc1 nt
	v_mov_b64_e32 v[78:79], v[10:11]
	v_mov_b64_e32 v[76:77], v[8:9]
	v_lshl_add_u64 v[84:85], v[82:83], 0, s[26:27]
	global_load_dwordx4 v[76:79], v[84:85], off sc0 sc1 nt
	v_lshl_add_u64 v[82:83], v[82:83], 0, s[28:29]
	global_load_dwordx4 v[8:11], v[82:83], off sc0 sc1 nt
	s_waitcnt vmcnt(9)
	v_lshl_add_u64 v[82:83], v[80:81], 0, s[16:17]
	global_store_dwordx4 v[82:83], v[12:15], off sc0 sc1 nt
	s_nop 1
	v_lshl_add_u64 v[12:13], v[82:83], 0, s[2:3]
	global_store_dwordx4 v[12:13], v[16:19], off sc0 sc1 nt
	s_nop 1
	v_lshl_add_u64 v[12:13], v[82:83], 0, s[6:7]
	global_store_dwordx4 v[12:13], v[20:23], off sc0 sc1 nt
	s_nop 1
	v_lshl_add_u64 v[12:13], v[82:83], 0, s[12:13]
	global_store_dwordx4 v[12:13], v[24:27], off sc0 sc1 nt
	s_nop 1
	v_lshl_add_u64 v[12:13], v[82:83], 0, s[14:15]
	global_store_dwordx4 v[12:13], v[28:31], off sc0 sc1 nt
	s_nop 1
	v_lshl_add_u64 v[12:13], v[82:83], 0, s[24:25]
	global_store_dwordx4 v[12:13], v[32:35], off sc0 sc1 nt
	s_nop 1
	v_lshl_add_u64 v[12:13], v[82:83], 0, s[0:1]
	global_store_dwordx4 v[12:13], v[36:39], off sc0 sc1 nt
	s_nop 1
	v_lshl_add_u64 v[12:13], v[82:83], 0, s[26:27]
	global_store_dwordx4 v[12:13], v[40:43], off sc0 sc1 nt
	s_nop 1
	v_lshl_add_u64 v[12:13], v[82:83], 0, s[28:29]
	global_store_dwordx4 v[12:13], v[44:47], off sc0 sc1 nt
	s_nop 1
	s_waitcnt vmcnt(0)
	v_lshl_add_u64 v[12:13], v[80:81], 0, s[10:11]
	global_store_dwordx4 v[12:13], v[48:51], off sc0 sc1 nt
	s_nop 1
	v_lshl_add_u64 v[14:15], v[12:13], 0, s[2:3]
	global_store_dwordx4 v[14:15], v[52:55], off sc0 sc1 nt
	s_nop 1
	v_lshl_add_u64 v[14:15], v[12:13], 0, s[6:7]
	global_store_dwordx4 v[14:15], v[56:59], off sc0 sc1 nt
	s_nop 1
	v_lshl_add_u64 v[14:15], v[12:13], 0, s[12:13]
	global_store_dwordx4 v[14:15], v[60:63], off sc0 sc1 nt
	s_nop 1
	v_lshl_add_u64 v[14:15], v[12:13], 0, s[14:15]
	global_store_dwordx4 v[14:15], v[64:67], off sc0 sc1 nt
	s_nop 1
	v_lshl_add_u64 v[14:15], v[12:13], 0, s[24:25]
	global_store_dwordx4 v[14:15], v[68:71], off sc0 sc1 nt
	s_nop 1
	v_lshl_add_u64 v[14:15], v[12:13], 0, s[0:1]
	global_store_dwordx4 v[14:15], v[72:75], off sc0 sc1 nt
	s_nop 1
	v_lshl_add_u64 v[14:15], v[12:13], 0, s[26:27]
	global_store_dwordx4 v[14:15], v[76:79], off sc0 sc1 nt
	s_nop 1
	v_lshl_add_u64 v[12:13], v[12:13], 0, s[28:29]
	global_store_dwordx4 v[12:13], v[8:11], off sc0 sc1 nt
	s_nop 1
	s_waitcnt vmcnt(0)
	s_mov_b64 s[10:11], 0
	s_branch .LBB0_369

.LBB0_471:
	v_add_u32_e32 v84, s2, v101
	v_and_b32_e32 v85, -16, v163
	s_movk_i32 s0, 0x180
	v_or_b32_e32 v36, v85, v159
	v_add_u32_e32 v37, 0x480, v84
	v_cmp_gt_i32_e32 vcc, s0, v84
	v_add_u32_e32 v52, v160, v85
	v_add_u32_e32 v53, 0x4a0, v84
	v_cndmask_b32_e32 v177, v37, v36, vcc
	v_mad_u64_u32 v[44:45], s[0:1], v177, s19, v[136:137]
	s_movk_i32 s0, 0x160
	s_nop 0
	v_cmp_gt_i32_e32 vcc, s0, v84
	v_add_u32_e32 v68, v161, v85
	v_add_u32_e32 v69, 0x4c0, v84
	v_cndmask_b32_e32 v176, v53, v52, vcc
	v_mad_u64_u32 v[60:61], s[0:1], v176, s19, v[136:137]
	s_movk_i32 s0, 0x140
	s_nop 0
	v_cmp_gt_i32_e32 vcc, s0, v84
	v_add_u32_e32 v85, v162, v85
	v_add_u32_e32 v86, 0x4e0, v84
	v_cndmask_b32_e32 v173, v69, v68, vcc
	v_mad_u64_u32 v[76:77], s[0:1], v173, s19, v[136:137]
	s_movk_i32 s0, 0x120
	s_nop 0
	v_cmp_gt_i32_e32 vcc, s0, v84
	v_add_u32_e32 v48, 0x1000, v44
	v_add_u32_e32 v64, 0x1000, v60
	v_cndmask_b32_e32 v172, v86, v85, vcc
	v_mad_u64_u32 v[92:93], s[0:1], v172, s19, v[136:137]
	v_add_u32_e32 v80, 0x1000, v76
	v_add_u32_e32 v96, 0x1000, v92
	buffer_load_dwordx4 v[36:39], v44, s[8:11], 0 offen sc0 nt sc1
	buffer_load_dwordx4 v[40:43], v44, s[8:11], 0 offen offset:256 sc0 nt sc1
	s_nop 0
	buffer_load_dwordx4 v[44:47], v48, s[8:11], 0 offen offset:2048 sc0 nt sc1
	s_nop 0
	buffer_load_dwordx4 v[48:51], v48, s[8:11], 0 offen offset:2304 sc0 nt sc1
	s_nop 0
	buffer_load_dwordx4 v[52:55], v60, s[8:11], 0 offen sc0 nt sc1
	buffer_load_dwordx4 v[56:59], v60, s[8:11], 0 offen offset:256 sc0 nt sc1
	s_nop 0
	buffer_load_dwordx4 v[60:63], v64, s[8:11], 0 offen offset:2048 sc0 nt sc1
	s_nop 0
	buffer_load_dwordx4 v[64:67], v64, s[8:11], 0 offen offset:2304 sc0 nt sc1
	s_nop 0
	buffer_load_dwordx4 v[68:71], v76, s[8:11], 0 offen sc0 nt sc1
	buffer_load_dwordx4 v[72:75], v76, s[8:11], 0 offen offset:256 sc0 nt sc1
	s_nop 0
	buffer_load_dwordx4 v[76:79], v80, s[8:11], 0 offen offset:2048 sc0 nt sc1
	s_nop 0
	buffer_load_dwordx4 v[80:83], v80, s[8:11], 0 offen offset:2304 sc0 nt sc1
	s_nop 0
	buffer_load_dwordx4 v[84:87], v92, s[8:11], 0 offen sc0 nt sc1
	buffer_load_dwordx4 v[88:91], v92, s[8:11], 0 offen offset:256 sc0 nt sc1
	s_nop 0
	buffer_load_dwordx4 v[92:95], v96, s[8:11], 0 offen offset:2048 sc0 nt sc1
	s_nop 0
	buffer_load_dwordx4 v[96:99], v96, s[8:11], 0 offen offset:2304 sc0 nt sc1
	s_waitcnt vmcnt(15)
	v_mul_f32_e32 v114, v37, v158
	v_fmac_f32_e32 v114, v36, v157
	v_fmac_f32_e32 v114, v38, v134
	v_fmac_f32_e32 v114, v39, v135
	s_waitcnt vmcnt(14)
	v_pk_mul_f32 v[112:113], v[40:41], v[132:133]
	v_mul_f32_e32 v115, v37, v156
	v_add_f32_e32 v112, v112, v114
	v_add_f32_e32 v114, v113, v112
	v_pk_mul_f32 v[112:113], v[42:43], v[130:131]
	v_fmac_f32_e32 v115, v36, v155
	v_add_f32_e32 v112, v112, v114
	v_add_f32_e32 v112, v113, v112
	v_fmac_f32_e32 v115, v38, v126
	v_fmac_f32_e32 v115, v39, v127
	v_add_f32_dpp v112, v112, v112 row_ror:8 row_mask:0xf bank_mask:0xf bound_ctrl:1
	v_mul_f32_e32 v128, v37, v152
	v_fmac_f32_e32 v128, v36, v151
	v_add_f32_dpp v112, v112, v112 row_ror:4 row_mask:0xf bank_mask:0xf bound_ctrl:1
	v_fmac_f32_e32 v128, v38, v110
	v_fmac_f32_e32 v128, v39, v111
	v_add_f32_dpp v168, v112, v112 row_ror:2 row_mask:0xf bank_mask:0xf bound_ctrl:1
	v_lshlrev_b32_e32 v112, 2, v177
	v_sub_u32_e32 v112, s51, v112
	v_add_u32_e32 v114, 0x2600, v112
	v_pk_mul_f32 v[112:113], v[40:41], v[124:125]
	s_waitcnt vmcnt(11)
	v_mul_f32_e32 v144, v53, v152
	v_add_f32_e32 v112, v112, v115
	v_add_f32_e32 v115, v113, v112
	v_pk_mul_f32 v[112:113], v[42:43], v[122:123]
	v_fmac_f32_e32 v144, v52, v151
	v_add_f32_e32 v112, v112, v115
	v_add_f32_e32 v112, v113, v112
	v_mul_f32_e32 v115, v37, v154
	v_fmac_f32_e32 v115, v36, v153
	v_add_f32_dpp v112, v112, v112 row_ror:8 row_mask:0xf bank_mask:0xf bound_ctrl:1
	v_fmac_f32_e32 v115, v38, v120
	v_fmac_f32_e32 v115, v39, v121
	v_add_f32_dpp v112, v112, v112 row_ror:4 row_mask:0xf bank_mask:0xf bound_ctrl:1
	v_fmac_f32_e32 v144, v54, v110
	v_fmac_f32_e32 v144, v55, v111
	v_add_f32_dpp v170, v112, v112 row_ror:2 row_mask:0xf bank_mask:0xf bound_ctrl:1
	v_pk_mul_f32 v[112:113], v[40:41], v[118:119]
	s_waitcnt vmcnt(7)
	v_mul_f32_e32 v145, v69, v156
	v_add_f32_e32 v112, v112, v115
	v_add_f32_e32 v115, v113, v112
	v_pk_mul_f32 v[112:113], v[42:43], v[116:117]
	v_fmac_f32_e32 v145, v68, v155
	v_add_f32_e32 v112, v112, v115
	v_add_f32_e32 v112, v113, v112
	v_fmac_f32_e32 v145, v70, v126
	v_fmac_f32_e32 v145, v71, v127
	v_add_f32_dpp v112, v112, v112 row_ror:8 row_mask:0xf bank_mask:0xf bound_ctrl:1
	v_mul_f32_e32 v146, v69, v152
	v_fmac_f32_e32 v146, v68, v151
	v_add_f32_dpp v112, v112, v112 row_ror:4 row_mask:0xf bank_mask:0xf bound_ctrl:1
	v_fmac_f32_e32 v146, v70, v110
	v_fmac_f32_e32 v146, v71, v111
	v_add_f32_dpp v174, v112, v112 row_ror:2 row_mask:0xf bank_mask:0xf bound_ctrl:1
	v_sub_u32_e32 v112, 2, v177
	v_lshl_add_u32 v112, v112, 2, s51
	v_add_u32_e32 v115, 0x2600, v112
	v_pk_mul_f32 v[112:113], v[40:41], v[108:109]
	s_waitcnt vmcnt(3)
	v_pk_mul_f32 v[212:213], v[86:87], v[110:111]
	v_add_f32_e32 v112, v112, v128
	v_add_f32_e32 v128, v113, v112
	v_pk_mul_f32 v[112:113], v[42:43], v[106:107]
	v_mov_b32_e32 v169, 0
	v_add_f32_e32 v112, v112, v128
	v_add_f32_e32 v112, v113, v112
	v_mul_f32_e32 v128, v53, v158
	v_fmac_f32_e32 v128, v52, v157
	v_add_f32_dpp v112, v112, v112 row_ror:8 row_mask:0xf bank_mask:0xf bound_ctrl:1
	v_fmac_f32_e32 v128, v54, v134
	v_fmac_f32_e32 v128, v55, v135
	v_add_f32_dpp v112, v112, v112 row_ror:4 row_mask:0xf bank_mask:0xf bound_ctrl:1
	v_mov_b32_e32 v171, 0
	v_mov_b32_e32 v175, 0
	v_add_f32_dpp v178, v112, v112 row_ror:2 row_mask:0xf bank_mask:0xf bound_ctrl:1
	v_pk_mul_f32 v[112:113], v[56:57], v[132:133]
	v_mov_b32_e32 v179, 0
	v_add_f32_e32 v112, v112, v128
	v_add_f32_e32 v128, v113, v112
	v_pk_mul_f32 v[112:113], v[58:59], v[130:131]
	v_mov_b32_e32 v181, 0
	v_add_f32_e32 v112, v112, v128
	v_add_f32_e32 v112, v113, v112
	v_mul_f32_e32 v128, v53, v156
	v_fmac_f32_e32 v128, v52, v155
	v_add_f32_dpp v112, v112, v112 row_ror:8 row_mask:0xf bank_mask:0xf bound_ctrl:1
	v_fmac_f32_e32 v128, v54, v126
	v_fmac_f32_e32 v128, v55, v127
	v_add_f32_dpp v112, v112, v112 row_ror:4 row_mask:0xf bank_mask:0xf bound_ctrl:1
	v_mov_b32_e32 v183, 0
	v_mov_b32_e32 v185, 0
	v_add_f32_dpp v180, v112, v112 row_ror:2 row_mask:0xf bank_mask:0xf bound_ctrl:1
	v_lshlrev_b32_e32 v112, 2, v176
	v_sub_u32_e32 v112, s51, v112
	v_add_u32_e32 v142, 0x2600, v112
	v_pk_mul_f32 v[112:113], v[56:57], v[124:125]
	v_mov_b32_e32 v187, 0
	v_add_f32_e32 v112, v112, v128
	v_add_f32_e32 v128, v113, v112
	v_pk_mul_f32 v[112:113], v[58:59], v[122:123]
	v_mov_b32_e32 v189, 0
	v_add_f32_e32 v112, v112, v128
	v_add_f32_e32 v112, v113, v112
	v_mul_f32_e32 v128, v53, v154
	v_fmac_f32_e32 v128, v52, v153
	v_add_f32_dpp v112, v112, v112 row_ror:8 row_mask:0xf bank_mask:0xf bound_ctrl:1
	v_fmac_f32_e32 v128, v54, v120
	v_fmac_f32_e32 v128, v55, v121
	v_add_f32_dpp v112, v112, v112 row_ror:4 row_mask:0xf bank_mask:0xf bound_ctrl:1
	v_mov_b32_e32 v191, 0
	v_mov_b32_e32 v193, 0
	v_add_f32_dpp v182, v112, v112 row_ror:2 row_mask:0xf bank_mask:0xf bound_ctrl:1
	v_pk_mul_f32 v[112:113], v[56:57], v[118:119]
	v_mov_b32_e32 v198, 0
	v_add_f32_e32 v112, v112, v128
	v_add_f32_e32 v128, v113, v112
	v_pk_mul_f32 v[112:113], v[58:59], v[116:117]
	v_mov_b32_e32 v200, 0
	v_add_f32_e32 v112, v112, v128
	v_add_f32_e32 v112, v113, v112
	v_mov_b32_e32 v202, 0
	v_mov_b32_e32 v210, 0
	v_add_f32_dpp v112, v112, v112 row_ror:8 row_mask:0xf bank_mask:0xf bound_ctrl:1
	v_mov_b32_dpp v169, v168 row_ror:1 row_mask:0xf bank_mask:0xf
	v_mov_b32_dpp v171, v170 row_ror:1 row_mask:0xf bank_mask:0xf
	v_add_f32_dpp v112, v112, v112 row_ror:4 row_mask:0xf bank_mask:0xf bound_ctrl:1
	v_mov_b32_dpp v175, v174 row_ror:1 row_mask:0xf bank_mask:0xf
	v_mov_b32_dpp v179, v178 row_ror:1 row_mask:0xf bank_mask:0xf
	v_add_f32_dpp v184, v112, v112 row_ror:2 row_mask:0xf bank_mask:0xf bound_ctrl:1
	v_sub_u32_e32 v112, 2, v176
	v_lshl_add_u32 v112, v112, 2, s51
	v_add_u32_e32 v112, 0x2600, v112
	ds_read2_b32 v[140:141], v114 offset1:1
	ds_read2_b32 v[128:129], v115 offset1:1
	ds_read2_b32 v[114:115], v142 offset1:1
	ds_read2_b32 v[112:113], v112 offset1:1
	v_pk_mul_f32 v[142:143], v[56:57], v[108:109]
	v_mov_b32_dpp v181, v180 row_ror:1 row_mask:0xf bank_mask:0xf
	v_add_f32_e32 v142, v142, v144
	v_add_f32_e32 v144, v143, v142
	v_pk_mul_f32 v[142:143], v[58:59], v[106:107]
	v_mov_b32_dpp v183, v182 row_ror:1 row_mask:0xf bank_mask:0xf
	v_add_f32_e32 v142, v142, v144
	v_add_f32_e32 v142, v143, v142
	v_mul_f32_e32 v144, v69, v158
	v_fmac_f32_e32 v144, v68, v157
	v_add_f32_dpp v142, v142, v142 row_ror:8 row_mask:0xf bank_mask:0xf bound_ctrl:1
	v_fmac_f32_e32 v144, v70, v134
	v_fmac_f32_e32 v144, v71, v135
	v_add_f32_dpp v142, v142, v142 row_ror:4 row_mask:0xf bank_mask:0xf bound_ctrl:1
	v_mov_b32_dpp v185, v184 row_ror:1 row_mask:0xf bank_mask:0xf
	s_nop 0
	v_add_f32_dpp v186, v142, v142 row_ror:2 row_mask:0xf bank_mask:0xf bound_ctrl:1
	v_pk_mul_f32 v[142:143], v[72:73], v[132:133]
	s_nop 0
	v_add_f32_e32 v142, v142, v144
	v_add_f32_e32 v144, v143, v142
	v_pk_mul_f32 v[142:143], v[74:75], v[130:131]
	v_mov_b32_dpp v187, v186 row_ror:1 row_mask:0xf bank_mask:0xf
	v_add_f32_e32 v142, v142, v144
	v_add_f32_e32 v142, v143, v142
	s_nop 1
	v_add_f32_dpp v142, v142, v142 row_ror:8 row_mask:0xf bank_mask:0xf bound_ctrl:1
	s_nop 1
	v_add_f32_dpp v142, v142, v142 row_ror:4 row_mask:0xf bank_mask:0xf bound_ctrl:1
	s_nop 1
	v_add_f32_dpp v188, v142, v142 row_ror:2 row_mask:0xf bank_mask:0xf bound_ctrl:1
	v_lshlrev_b32_e32 v142, 2, v173
	v_sub_u32_e32 v142, s51, v142
	v_add_u32_e32 v144, 0x2600, v142
	v_pk_mul_f32 v[142:143], v[72:73], v[124:125]
	v_mov_b32_dpp v189, v188 row_ror:1 row_mask:0xf bank_mask:0xf
	v_add_f32_e32 v142, v142, v145
	v_add_f32_e32 v145, v143, v142
	v_pk_mul_f32 v[142:143], v[74:75], v[122:123]
	s_nop 0
	v_add_f32_e32 v142, v142, v145
	v_add_f32_e32 v142, v143, v142
	v_mul_f32_e32 v145, v69, v154
	v_fmac_f32_e32 v145, v68, v153
	v_add_f32_dpp v142, v142, v142 row_ror:8 row_mask:0xf bank_mask:0xf bound_ctrl:1
	v_fmac_f32_e32 v145, v70, v120
	v_fmac_f32_e32 v145, v71, v121
	v_add_f32_dpp v142, v142, v142 row_ror:4 row_mask:0xf bank_mask:0xf bound_ctrl:1
	s_nop 1
	v_add_f32_dpp v190, v142, v142 row_ror:2 row_mask:0xf bank_mask:0xf bound_ctrl:1
	v_pk_mul_f32 v[142:143], v[72:73], v[118:119]
	s_nop 0
	v_add_f32_e32 v142, v142, v145
	v_add_f32_e32 v145, v143, v142
	v_pk_mul_f32 v[142:143], v[74:75], v[116:117]
	v_mov_b32_dpp v191, v190 row_ror:1 row_mask:0xf bank_mask:0xf
	v_add_f32_e32 v142, v142, v145
	v_add_f32_e32 v142, v143, v142
	s_nop 1
	v_add_f32_dpp v142, v142, v142 row_ror:8 row_mask:0xf bank_mask:0xf bound_ctrl:1
	s_nop 1
	v_add_f32_dpp v142, v142, v142 row_ror:4 row_mask:0xf bank_mask:0xf bound_ctrl:1
	s_nop 1
	v_add_f32_dpp v192, v142, v142 row_ror:2 row_mask:0xf bank_mask:0xf bound_ctrl:1
	v_sub_u32_e32 v142, 2, v173
	v_lshl_add_u32 v142, v142, 2, s51
	v_add_u32_e32 v145, 0x2600, v142
	v_pk_mul_f32 v[142:143], v[72:73], v[108:109]
	v_mov_b32_dpp v193, v192 row_ror:1 row_mask:0xf bank_mask:0xf
	v_add_f32_e32 v142, v142, v146
	v_add_f32_e32 v146, v143, v142
	v_pk_mul_f32 v[142:143], v[74:75], v[106:107]
	s_nop 0
	v_add_f32_e32 v142, v142, v146
	v_add_f32_e32 v142, v143, v142
	v_mul_f32_e32 v146, v85, v158
	v_fmac_f32_e32 v146, v84, v157
	v_add_f32_dpp v142, v142, v142 row_ror:8 row_mask:0xf bank_mask:0xf bound_ctrl:1
	s_nop 1
	v_add_f32_dpp v142, v142, v142 row_ror:4 row_mask:0xf bank_mask:0xf bound_ctrl:1
	s_nop 1
	v_add_f32_dpp v197, v142, v142 row_ror:2 row_mask:0xf bank_mask:0xf bound_ctrl:1
	v_pk_mul_f32 v[142:143], v[86:87], v[134:135]
	s_nop 0
	v_add_f32_e32 v142, v142, v146
	v_add_f32_e32 v146, v143, v142
	s_waitcnt vmcnt(2)
	v_pk_mul_f32 v[142:143], v[88:89], v[132:133]
	v_mov_b32_dpp v198, v197 row_ror:1 row_mask:0xf bank_mask:0xf
	v_add_f32_e32 v142, v142, v146
	v_add_f32_e32 v146, v143, v142
	v_pk_mul_f32 v[142:143], v[90:91], v[130:131]
	s_nop 0
	v_add_f32_e32 v142, v142, v146
	v_add_f32_e32 v142, v143, v142
	v_mul_f32_e32 v146, v85, v156
	v_fmac_f32_e32 v146, v84, v155
	v_add_f32_dpp v142, v142, v142 row_ror:8 row_mask:0xf bank_mask:0xf bound_ctrl:1
	s_nop 1
	v_add_f32_dpp v142, v142, v142 row_ror:4 row_mask:0xf bank_mask:0xf bound_ctrl:1
	s_nop 1
	v_add_f32_dpp v199, v142, v142 row_ror:2 row_mask:0xf bank_mask:0xf bound_ctrl:1
	v_lshlrev_b32_e32 v142, 2, v172
	v_sub_u32_e32 v142, s51, v142
	v_add_u32_e32 v211, 0x2600, v142
	v_pk_mul_f32 v[142:143], v[86:87], v[126:127]
	v_mov_b32_dpp v200, v199 row_ror:1 row_mask:0xf bank_mask:0xf
	v_add_f32_e32 v142, v142, v146
	v_add_f32_e32 v146, v143, v142
	v_pk_mul_f32 v[142:143], v[88:89], v[124:125]
	s_nop 0
	v_add_f32_e32 v142, v142, v146
	v_add_f32_e32 v146, v143, v142
	v_pk_mul_f32 v[142:143], v[90:91], v[122:123]
	s_nop 0
	v_add_f32_e32 v142, v142, v146
	v_add_f32_e32 v142, v143, v142
	v_mul_f32_e32 v146, v85, v154
	v_fmac_f32_e32 v146, v84, v153
	v_add_f32_dpp v142, v142, v142 row_ror:8 row_mask:0xf bank_mask:0xf bound_ctrl:1
	s_nop 1
	v_add_f32_dpp v142, v142, v142 row_ror:4 row_mask:0xf bank_mask:0xf bound_ctrl:1
	s_nop 1
	v_add_f32_dpp v201, v142, v142 row_ror:2 row_mask:0xf bank_mask:0xf bound_ctrl:1
	v_pk_mul_f32 v[142:143], v[86:87], v[120:121]
	s_nop 0
	v_add_f32_e32 v142, v142, v146
	v_add_f32_e32 v146, v143, v142
	v_pk_mul_f32 v[142:143], v[88:89], v[118:119]
	v_mov_b32_dpp v202, v201 row_ror:1 row_mask:0xf bank_mask:0xf
	v_add_f32_e32 v142, v142, v146
	v_add_f32_e32 v146, v143, v142
	v_pk_mul_f32 v[142:143], v[90:91], v[116:117]
	s_nop 0
	v_add_f32_e32 v142, v142, v146
	v_add_f32_e32 v142, v143, v142
	s_nop 1
	v_add_f32_dpp v142, v142, v142 row_ror:8 row_mask:0xf bank_mask:0xf bound_ctrl:1
	s_nop 1
	v_add_f32_dpp v142, v142, v142 row_ror:4 row_mask:0xf bank_mask:0xf bound_ctrl:1
	s_nop 1
	v_add_f32_dpp v203, v142, v142 row_ror:2 row_mask:0xf bank_mask:0xf bound_ctrl:1
	v_sub_u32_e32 v142, 2, v172
	v_lshl_add_u32 v142, v142, 2, s51
	v_add_u32_e32 v142, 0x2600, v142
	ds_read2_b32 v[148:149], v144 offset1:1
	ds_read2_b32 v[146:147], v145 offset1:1
	ds_read2_b32 v[144:145], v211 offset1:1
	ds_read2_b32 v[142:143], v142 offset1:1
	v_mul_f32_e32 v211, v85, v152
	v_fmac_f32_e32 v211, v84, v151
	v_add_f32_e32 v211, v212, v211
	v_add_f32_e32 v211, v213, v211
	v_pk_mul_f32 v[212:213], v[88:89], v[108:109]
	v_mov_b32_dpp v210, v203 row_ror:1 row_mask:0xf bank_mask:0xf
	v_add_f32_e32 v211, v212, v211
	v_add_f32_e32 v211, v213, v211
	v_pk_mul_f32 v[212:213], v[90:91], v[106:107]
	s_waitcnt vmcnt(0)
	v_add_f32_e32 v211, v212, v211
	v_add_f32_e32 v211, v213, v211
	v_mov_b32_e32 v212, 0
	s_nop 0
	v_add_f32_dpp v211, v211, v211 row_ror:8 row_mask:0xf bank_mask:0xf bound_ctrl:1
	s_nop 1
	v_add_f32_dpp v211, v211, v211 row_ror:4 row_mask:0xf bank_mask:0xf bound_ctrl:1
	s_nop 1
	v_add_f32_dpp v211, v211, v211 row_ror:2 row_mask:0xf bank_mask:0xf bound_ctrl:1
	s_nop 1
	v_mov_b32_dpp v212, v211 row_ror:1 row_mask:0xf bank_mask:0xf
	v_cmp_lt_i32_e32 vcc, 3, v177
	s_and_saveexec_b64 s[0:1], vcc
	s_cbranch_execz .LBB0_475
	v_add_u32_e32 v177, -4, v177
	v_mad_u64_u32 v[214:215], s[12:13], v177, s19, v[138:139]
	global_store_dwordx4 v[214:215], v[36:39], off sc0 sc1 nt
	s_nop 1
	v_lshl_add_u64 v[216:217], v[214:215], 0, s[26:27]
	global_store_dwordx4 v[216:217], v[40:43], off sc0 sc1 nt
	s_nop 1
	v_lshl_add_u64 v[216:217], v[214:215], 0, s[28:29]
	global_store_dwordx4 v[216:217], v[44:47], off sc0 sc1 nt
	s_nop 1
	v_lshl_add_u64 v[214:215], v[214:215], 0, s[34:35]
	global_store_dwordx4 v[214:215], v[48:51], off sc0 sc1 nt
	s_nop 1
	s_or_b64 exec, exec, s[0:1]
	v_cmp_lt_i32_e32 vcc, 3, v176
	s_and_saveexec_b64 s[0:1], vcc
	s_cbranch_execnz .LBB0_476

.LBB0_474:
	v_add_u32_e32 v173, -4, v173
	v_mad_u64_u32 v[176:177], s[12:13], v173, s19, v[138:139]
	global_store_dwordx4 v[176:177], v[68:71], off sc0 sc1 nt
	s_nop 1
	v_lshl_add_u64 v[214:215], v[176:177], 0, s[26:27]
	global_store_dwordx4 v[214:215], v[72:75], off sc0 sc1 nt
	s_nop 1
	v_lshl_add_u64 v[214:215], v[176:177], 0, s[28:29]
	global_store_dwordx4 v[214:215], v[76:79], off sc0 sc1 nt
	s_nop 1
	v_lshl_add_u64 v[176:177], v[176:177], 0, s[34:35]
	global_store_dwordx4 v[176:177], v[80:83], off sc0 sc1 nt
	s_nop 1
	s_or_b64 exec, exec, s[0:1]
	v_cmp_lt_i32_e32 vcc, 3, v172
	s_and_saveexec_b64 s[0:1], vcc
	s_cbranch_execnz .LBB0_478
	s_branch .LBB0_479

.LBB0_476:
	v_add_u32_e32 v176, -4, v176
	v_mad_u64_u32 v[176:177], s[12:13], v176, s19, v[138:139]
	global_store_dwordx4 v[176:177], v[52:55], off sc0 sc1 nt
	s_nop 1
	v_lshl_add_u64 v[214:215], v[176:177], 0, s[26:27]
	global_store_dwordx4 v[214:215], v[56:59], off sc0 sc1 nt
	s_nop 1
	v_lshl_add_u64 v[214:215], v[176:177], 0, s[28:29]
	global_store_dwordx4 v[214:215], v[60:63], off sc0 sc1 nt
	s_nop 1
	v_lshl_add_u64 v[176:177], v[176:177], 0, s[34:35]
	global_store_dwordx4 v[176:177], v[64:67], off sc0 sc1 nt
	s_nop 1
	s_or_b64 exec, exec, s[0:1]
	v_cmp_lt_i32_e32 vcc, 3, v173
	s_and_saveexec_b64 s[0:1], vcc
	s_cbranch_execnz .LBB0_474

.LBB0_478:
	v_add_u32_e32 v172, -4, v172
	v_mad_u64_u32 v[172:173], s[12:13], v172, s19, v[138:139]
	global_store_dwordx4 v[172:173], v[84:87], off sc0 sc1 nt
	s_nop 1
	v_lshl_add_u64 v[176:177], v[172:173], 0, s[26:27]
	global_store_dwordx4 v[176:177], v[88:91], off sc0 sc1 nt
	s_nop 1
	v_lshl_add_u64 v[176:177], v[172:173], 0, s[28:29]
	global_store_dwordx4 v[176:177], v[92:95], off sc0 sc1 nt
	s_nop 1
	v_lshl_add_u64 v[172:173], v[172:173], 0, s[34:35]
	global_store_dwordx4 v[172:173], v[96:99], off sc0 sc1 nt
	s_nop 1

.LBB0_607:
	s_or_b64 exec, exec, s[10:11]
	s_waitcnt lgkmcnt(0)
	s_barrier
	ds_read_b32 v8, v1
	s_mov_b64 s[10:11], -1
	s_waitcnt lgkmcnt(0)
	v_readfirstlane_b32 s9, v8
	s_cmpk_gt_i32 s9, 0x5ff
	s_cbranch_scc1 .LBB0_600
	s_mul_hi_i32 s10, s9, 0x2aaaaaab
	s_lshr_b32 s11, s10, 31
	s_add_i32 s16, s10, s11
	s_mul_i32 s10, s16, 6
	s_sub_i32 s9, s9, s10
	s_ashr_i32 s17, s16, 3
	s_add_i32 s9, s9, 6
	v_mad_i64_i32 v[8:9], s[10:11], s17, v2, v[4:5]
	s_and_b32 s16, s16, 7
	v_mad_i64_i32 v[80:81], s[10:11], s17, v2, v[6:7]
	s_mul_i32 s16, s16, 0x24000
	s_mul_hi_u32 s11, s9, 0x3000
	s_mulk_i32 s9, 0x3000
	s_add_u32 s10, s9, s16
	s_addc_u32 s11, s11, 0
	s_lshl_b64 s[16:17], s[10:11], 4
	s_mov_b32 s10, s8
	s_mov_b32 s11, s8
	v_lshl_add_u64 v[48:49], v[8:9], 0, s[0:1]
	s_mov_b32 s9, s8
	v_mov_b64_e32 v[14:15], s[10:11]
	s_waitcnt vmcnt(0)
	v_lshl_add_u64 v[44:45], v[48:49], 0, s[16:17]
	v_mov_b64_e32 v[12:13], s[8:9]
	v_mov_b64_e32 v[18:19], s[10:11]
	global_load_dwordx4 v[12:15], v[44:45], off sc0 sc1 nt
	v_lshl_add_u64 v[20:21], v[44:45], 0, s[2:3]
	v_mov_b64_e32 v[16:17], s[8:9]
	global_load_dwordx4 v[16:19], v[20:21], off sc0 sc1 nt
	v_mov_b64_e32 v[22:23], s[10:11]
	v_lshl_add_u64 v[24:25], v[44:45], 0, s[6:7]
	v_mov_b64_e32 v[20:21], s[8:9]
	global_load_dwordx4 v[20:23], v[24:25], off sc0 sc1 nt
	v_mov_b64_e32 v[26:27], s[10:11]
	v_lshl_add_u64 v[28:29], v[44:45], 0, s[12:13]
	v_mov_b64_e32 v[24:25], s[8:9]
	global_load_dwordx4 v[24:27], v[28:29], off sc0 sc1 nt
	v_mov_b64_e32 v[30:31], s[10:11]
	v_lshl_add_u64 v[32:33], v[44:45], 0, s[14:15]
	v_mov_b64_e32 v[28:29], s[8:9]
	global_load_dwordx4 v[28:31], v[32:33], off sc0 sc1 nt
	v_mov_b64_e32 v[34:35], s[10:11]
	v_lshl_add_u64 v[36:37], v[44:45], 0, s[20:21]
	v_mov_b64_e32 v[32:33], s[8:9]
	global_load_dwordx4 v[32:35], v[36:37], off sc0 sc1 nt
	v_mov_b64_e32 v[38:39], s[10:11]
	v_lshl_add_u64 v[40:41], v[44:45], 0, s[0:1]
	v_mov_b64_e32 v[36:37], s[8:9]
	global_load_dwordx4 v[36:39], v[40:41], off sc0 sc1 nt
	v_mov_b64_e32 v[42:43], s[10:11]
	v_lshl_add_u64 v[46:47], v[44:45], 0, s[24:25]
	v_mov_b64_e32 v[40:41], s[8:9]
	v_mov_b64_e32 v[8:9], s[8:9]
	global_load_dwordx4 v[40:43], v[46:47], off sc0 sc1 nt
	v_lshl_add_u64 v[50:51], v[44:45], 0, s[26:27]
	v_mov_b64_e32 v[46:47], s[10:11]
	v_mov_b64_e32 v[10:11], s[10:11]
	v_mov_b64_e32 v[44:45], s[8:9]
	s_add_u32 s10, s16, 0x12000
	s_addc_u32 s11, s17, 0
	global_load_dwordx4 v[44:47], v[50:51], off sc0 sc1 nt
	v_lshl_add_u64 v[82:83], v[48:49], 0, s[10:11]
	v_mov_b64_e32 v[50:51], v[10:11]
	v_mov_b64_e32 v[48:49], v[8:9]
	v_mov_b64_e32 v[54:55], v[10:11]
	global_load_dwordx4 v[48:51], v[82:83], off sc0 sc1 nt
	v_lshl_add_u64 v[56:57], v[82:83], 0, s[2:3]
	v_mov_b64_e32 v[52:53], v[8:9]
	global_load_dwordx4 v[52:55], v[56:57], off sc0 sc1 nt
	v_mov_b64_e32 v[58:59], v[10:11]
	v_lshl_add_u64 v[60:61], v[82:83], 0, s[6:7]
	v_mov_b64_e32 v[56:57], v[8:9]
	global_load_dwordx4 v[56:59], v[60:61], off sc0 sc1 nt
	v_mov_b64_e32 v[62:63], v[10:11]
	v_lshl_add_u64 v[64:65], v[82:83], 0, s[12:13]
	v_mov_b64_e32 v[60:61], v[8:9]
	global_load_dwordx4 v[60:63], v[64:65], off sc0 sc1 nt
	v_mov_b64_e32 v[66:67], v[10:11]
	v_lshl_add_u64 v[68:69], v[82:83], 0, s[14:15]
	v_mov_b64_e32 v[64:65], v[8:9]
	global_load_dwordx4 v[64:67], v[68:69], off sc0 sc1 nt
	v_mov_b64_e32 v[70:71], v[10:11]
	v_lshl_add_u64 v[72:73], v[82:83], 0, s[20:21]
	v_mov_b64_e32 v[68:69], v[8:9]
	global_load_dwordx4 v[68:71], v[72:73], off sc0 sc1 nt
	v_mov_b64_e32 v[74:75], v[10:11]
	v_lshl_add_u64 v[76:77], v[82:83], 0, s[0:1]
	v_mov_b64_e32 v[72:73], v[8:9]
	global_load_dwordx4 v[72:75], v[76:77], off sc0 sc1 nt
	v_mov_b64_e32 v[78:79], v[10:11]
	v_mov_b64_e32 v[76:77], v[8:9]
	v_lshl_add_u64 v[84:85], v[82:83], 0, s[24:25]
	global_load_dwordx4 v[76:79], v[84:85], off sc0 sc1 nt
	v_lshl_add_u64 v[82:83], v[82:83], 0, s[26:27]
	global_load_dwordx4 v[8:11], v[82:83], off sc0 sc1 nt
	s_waitcnt vmcnt(9)
	v_lshl_add_u64 v[82:83], v[80:81], 0, s[16:17]
	global_store_dwordx4 v[82:83], v[12:15], off sc0 sc1 nt
	s_nop 1
	v_lshl_add_u64 v[12:13], v[82:83], 0, s[2:3]
	global_store_dwordx4 v[12:13], v[16:19], off sc0 sc1 nt
	s_nop 1
	v_lshl_add_u64 v[12:13], v[82:83], 0, s[6:7]
	global_store_dwordx4 v[12:13], v[20:23], off sc0 sc1 nt
	s_nop 1
	v_lshl_add_u64 v[12:13], v[82:83], 0, s[12:13]
	global_store_dwordx4 v[12:13], v[24:27], off sc0 sc1 nt
	s_nop 1
	v_lshl_add_u64 v[12:13], v[82:83], 0, s[14:15]
	global_store_dwordx4 v[12:13], v[28:31], off sc0 sc1 nt
	s_nop 1
	v_lshl_add_u64 v[12:13], v[82:83], 0, s[20:21]
	global_store_dwordx4 v[12:13], v[32:35], off sc0 sc1 nt
	s_nop 1
	v_lshl_add_u64 v[12:13], v[82:83], 0, s[0:1]
	global_store_dwordx4 v[12:13], v[36:39], off sc0 sc1 nt
	s_nop 1
	v_lshl_add_u64 v[12:13], v[82:83], 0, s[24:25]
	global_store_dwordx4 v[12:13], v[40:43], off sc0 sc1 nt
	s_nop 1
	v_lshl_add_u64 v[12:13], v[82:83], 0, s[26:27]
	global_store_dwordx4 v[12:13], v[44:47], off sc0 sc1 nt
	s_nop 1
	s_waitcnt vmcnt(0)
	v_lshl_add_u64 v[12:13], v[80:81], 0, s[10:11]
	global_store_dwordx4 v[12:13], v[48:51], off sc0 sc1 nt
	s_nop 1
	v_lshl_add_u64 v[14:15], v[12:13], 0, s[2:3]
	global_store_dwordx4 v[14:15], v[52:55], off sc0 sc1 nt
	s_nop 1
	v_lshl_add_u64 v[14:15], v[12:13], 0, s[6:7]
	global_store_dwordx4 v[14:15], v[56:59], off sc0 sc1 nt
	s_nop 1
	v_lshl_add_u64 v[14:15], v[12:13], 0, s[12:13]
	global_store_dwordx4 v[14:15], v[60:63], off sc0 sc1 nt
	s_nop 1
	v_lshl_add_u64 v[14:15], v[12:13], 0, s[14:15]
	global_store_dwordx4 v[14:15], v[64:67], off sc0 sc1 nt
	s_nop 1
	v_lshl_add_u64 v[14:15], v[12:13], 0, s[20:21]
	global_store_dwordx4 v[14:15], v[68:71], off sc0 sc1 nt
	s_nop 1
	v_lshl_add_u64 v[14:15], v[12:13], 0, s[0:1]
	global_store_dwordx4 v[14:15], v[72:75], off sc0 sc1 nt
	s_nop 1
	v_lshl_add_u64 v[14:15], v[12:13], 0, s[24:25]
	global_store_dwordx4 v[14:15], v[76:79], off sc0 sc1 nt
	s_nop 1
	v_lshl_add_u64 v[12:13], v[12:13], 0, s[26:27]
	global_store_dwordx4 v[12:13], v[8:11], off sc0 sc1 nt
	s_nop 1
	s_waitcnt vmcnt(0)
	s_mov_b64 s[10:11], 0
	s_branch .LBB0_600
